# phase 0 adaLN GEMV: 32-64 weight loads in flight per wave (was 8 per iteration with a full drain in each of 16 iterations)
# speedup vs baseline: 1.0312x; 1.0100x over previous
.LBB0_29:
	s_lshl_b64 s[98:99], s[12:13], 2
	s_add_u32 s98, s98, s4
	s_addc_u32 s99, s99, s5
	v_add_u32_e32 v200, v20, v22
	global_load_dword v80, v200, s[98:99]
	s_add_u32 s98, s98, 0x6000
	s_addc_u32 s99, s99, 0
	global_load_dword v81, v200, s[98:99]
	s_add_u32 s98, s98, 0x6000
	s_addc_u32 s99, s99, 0
	global_load_dword v82, v200, s[98:99]
	s_add_u32 s98, s98, 0x6000
	s_addc_u32 s99, s99, 0
	global_load_dword v83, v200, s[98:99]
	s_add_u32 s98, s98, 0x6000
	s_addc_u32 s99, s99, 0
	global_load_dword v84, v200, s[98:99]
	s_add_u32 s98, s98, 0x6000
	s_addc_u32 s99, s99, 0
	global_load_dword v85, v200, s[98:99]
	s_add_u32 s98, s98, 0x6000
	s_addc_u32 s99, s99, 0
	global_load_dword v86, v200, s[98:99]
	s_add_u32 s98, s98, 0x6000
	s_addc_u32 s99, s99, 0
	global_load_dword v87, v200, s[98:99]
	s_add_u32 s98, s98, 0x6000
	s_addc_u32 s99, s99, 0
	global_load_dword v88, v200, s[98:99]
	s_add_u32 s98, s98, 0x6000
	s_addc_u32 s99, s99, 0
	global_load_dword v89, v200, s[98:99]
	s_add_u32 s98, s98, 0x6000
	s_addc_u32 s99, s99, 0
	global_load_dword v90, v200, s[98:99]
	s_add_u32 s98, s98, 0x6000
	s_addc_u32 s99, s99, 0
	global_load_dword v91, v200, s[98:99]
	s_add_u32 s98, s98, 0x6000
	s_addc_u32 s99, s99, 0
	global_load_dword v92, v200, s[98:99]
	s_add_u32 s98, s98, 0x6000
	s_addc_u32 s99, s99, 0
	global_load_dword v93, v200, s[98:99]
	s_add_u32 s98, s98, 0x6000
	s_addc_u32 s99, s99, 0
	global_load_dword v94, v200, s[98:99]
	s_add_u32 s98, s98, 0x6000
	s_addc_u32 s99, s99, 0
	global_load_dword v95, v200, s[98:99]
	s_add_u32 s98, s98, 0x6000
	s_addc_u32 s99, s99, 0
	global_load_dword v96, v200, s[98:99]
	s_add_u32 s98, s98, 0x6000
	s_addc_u32 s99, s99, 0
	global_load_dword v97, v200, s[98:99]
	s_add_u32 s98, s98, 0x6000
	s_addc_u32 s99, s99, 0
	global_load_dword v98, v200, s[98:99]
	s_add_u32 s98, s98, 0x6000
	s_addc_u32 s99, s99, 0
	global_load_dword v99, v200, s[98:99]
	s_add_u32 s98, s98, 0x6000
	s_addc_u32 s99, s99, 0
	global_load_dword v100, v200, s[98:99]
	s_add_u32 s98, s98, 0x6000
	s_addc_u32 s99, s99, 0
	global_load_dword v101, v200, s[98:99]
	s_add_u32 s98, s98, 0x6000
	s_addc_u32 s99, s99, 0
	global_load_dword v102, v200, s[98:99]
	s_add_u32 s98, s98, 0x6000
	s_addc_u32 s99, s99, 0
	global_load_dword v103, v200, s[98:99]
	s_add_u32 s98, s98, 0x6000
	s_addc_u32 s99, s99, 0
	global_load_dword v104, v200, s[98:99]
	s_add_u32 s98, s98, 0x6000
	s_addc_u32 s99, s99, 0
	global_load_dword v105, v200, s[98:99]
	s_add_u32 s98, s98, 0x6000
	s_addc_u32 s99, s99, 0
	global_load_dword v106, v200, s[98:99]
	s_add_u32 s98, s98, 0x6000
	s_addc_u32 s99, s99, 0
	global_load_dword v107, v200, s[98:99]
	s_add_u32 s98, s98, 0x6000
	s_addc_u32 s99, s99, 0
	global_load_dword v108, v200, s[98:99]
	s_add_u32 s98, s98, 0x6000
	s_addc_u32 s99, s99, 0
	global_load_dword v109, v200, s[98:99]
	s_add_u32 s98, s98, 0x6000
	s_addc_u32 s99, s99, 0
	global_load_dword v110, v200, s[98:99]
	s_add_u32 s98, s98, 0x6000
	s_addc_u32 s99, s99, 0
	global_load_dword v111, v200, s[98:99]
	s_add_u32 s98, s98, 0x6000
	s_addc_u32 s99, s99, 0
	global_load_dword v112, v200, s[98:99]
	s_add_u32 s98, s98, 0x6000
	s_addc_u32 s99, s99, 0
	global_load_dword v113, v200, s[98:99]
	s_add_u32 s98, s98, 0x6000
	s_addc_u32 s99, s99, 0
	global_load_dword v114, v200, s[98:99]
	s_add_u32 s98, s98, 0x6000
	s_addc_u32 s99, s99, 0
	global_load_dword v115, v200, s[98:99]
	s_add_u32 s98, s98, 0x6000
	s_addc_u32 s99, s99, 0
	global_load_dword v116, v200, s[98:99]
	s_add_u32 s98, s98, 0x6000
	s_addc_u32 s99, s99, 0
	global_load_dword v117, v200, s[98:99]
	s_add_u32 s98, s98, 0x6000
	s_addc_u32 s99, s99, 0
	global_load_dword v118, v200, s[98:99]
	s_add_u32 s98, s98, 0x6000
	s_addc_u32 s99, s99, 0
	global_load_dword v119, v200, s[98:99]
	s_add_u32 s98, s98, 0x6000
	s_addc_u32 s99, s99, 0
	global_load_dword v120, v200, s[98:99]
	s_add_u32 s98, s98, 0x6000
	s_addc_u32 s99, s99, 0
	global_load_dword v121, v200, s[98:99]
	s_add_u32 s98, s98, 0x6000
	s_addc_u32 s99, s99, 0
	global_load_dword v122, v200, s[98:99]
	s_add_u32 s98, s98, 0x6000
	s_addc_u32 s99, s99, 0
	global_load_dword v123, v200, s[98:99]
	s_add_u32 s98, s98, 0x6000
	s_addc_u32 s99, s99, 0
	global_load_dword v124, v200, s[98:99]
	s_add_u32 s98, s98, 0x6000
	s_addc_u32 s99, s99, 0
	global_load_dword v125, v200, s[98:99]
	s_add_u32 s98, s98, 0x6000
	s_addc_u32 s99, s99, 0
	global_load_dword v126, v200, s[98:99]
	s_add_u32 s98, s98, 0x6000
	s_addc_u32 s99, s99, 0
	global_load_dword v127, v200, s[98:99]
	s_add_u32 s98, s98, 0x6000
	s_addc_u32 s99, s99, 0
	global_load_dword v128, v200, s[98:99]
	s_add_u32 s98, s98, 0x6000
	s_addc_u32 s99, s99, 0
	global_load_dword v129, v200, s[98:99]
	s_add_u32 s98, s98, 0x6000
	s_addc_u32 s99, s99, 0
	global_load_dword v130, v200, s[98:99]
	s_add_u32 s98, s98, 0x6000
	s_addc_u32 s99, s99, 0
	global_load_dword v131, v200, s[98:99]
	s_add_u32 s98, s98, 0x6000
	s_addc_u32 s99, s99, 0
	global_load_dword v132, v200, s[98:99]
	s_add_u32 s98, s98, 0x6000
	s_addc_u32 s99, s99, 0
	global_load_dword v133, v200, s[98:99]
	s_add_u32 s98, s98, 0x6000
	s_addc_u32 s99, s99, 0
	global_load_dword v134, v200, s[98:99]
	s_add_u32 s98, s98, 0x6000
	s_addc_u32 s99, s99, 0
	global_load_dword v135, v200, s[98:99]
	s_add_u32 s98, s98, 0x6000
	s_addc_u32 s99, s99, 0
	global_load_dword v136, v200, s[98:99]
	s_add_u32 s98, s98, 0x6000
	s_addc_u32 s99, s99, 0
	global_load_dword v137, v200, s[98:99]
	s_add_u32 s98, s98, 0x6000
	s_addc_u32 s99, s99, 0
	global_load_dword v138, v200, s[98:99]
	s_add_u32 s98, s98, 0x6000
	s_addc_u32 s99, s99, 0
	global_load_dword v139, v200, s[98:99]
	s_add_u32 s98, s98, 0x6000
	s_addc_u32 s99, s99, 0
	global_load_dword v140, v200, s[98:99]
	s_add_u32 s98, s98, 0x6000
	s_addc_u32 s99, s99, 0
	global_load_dword v141, v200, s[98:99]
	s_add_u32 s98, s98, 0x6000
	s_addc_u32 s99, s99, 0
	global_load_dword v142, v200, s[98:99]
	s_add_u32 s98, s98, 0x6000
	s_addc_u32 s99, s99, 0
	global_load_dword v143, v200, s[98:99]
	s_add_u32 s98, s98, 0x6000
	s_addc_u32 s99, s99, 0
	ds_read_b128 v[144:147], v35
	ds_read_b128 v[148:151], v35 offset:4096
	ds_read_b128 v[152:155], v35 offset:8192
	s_waitcnt vmcnt(32)
	ds_read_b128 v[156:159], v35 offset:16
	ds_read_b128 v[160:163], v35 offset:4112
	ds_read_b128 v[164:167], v35 offset:8208
	s_waitcnt lgkmcnt(3)
	v_fmac_f32_e32 v30, v80, v144
	v_fmac_f32_e32 v34, v80, v148
	v_fmac_f32_e32 v31, v80, v152
	v_fmac_f32_e32 v30, v81, v145
	v_fmac_f32_e32 v34, v81, v149
	v_fmac_f32_e32 v31, v81, v153
	v_fmac_f32_e32 v30, v82, v146
	v_fmac_f32_e32 v34, v82, v150
	v_fmac_f32_e32 v31, v82, v154
	v_fmac_f32_e32 v30, v83, v147
	v_fmac_f32_e32 v34, v83, v151
	v_fmac_f32_e32 v31, v83, v155
	ds_read_b128 v[144:147], v35 offset:32
	ds_read_b128 v[148:151], v35 offset:4128
	ds_read_b128 v[152:155], v35 offset:8224
	s_waitcnt lgkmcnt(3)
	v_fmac_f32_e32 v30, v84, v156
	v_fmac_f32_e32 v34, v84, v160
	v_fmac_f32_e32 v31, v84, v164
	v_fmac_f32_e32 v30, v85, v157
	v_fmac_f32_e32 v34, v85, v161
	v_fmac_f32_e32 v31, v85, v165
	v_fmac_f32_e32 v30, v86, v158
	v_fmac_f32_e32 v34, v86, v162
	v_fmac_f32_e32 v31, v86, v166
	v_fmac_f32_e32 v30, v87, v159
	v_fmac_f32_e32 v34, v87, v163
	v_fmac_f32_e32 v31, v87, v167
	ds_read_b128 v[156:159], v35 offset:48
	ds_read_b128 v[160:163], v35 offset:4144
	ds_read_b128 v[164:167], v35 offset:8240
	s_waitcnt lgkmcnt(3)
	v_fmac_f32_e32 v30, v88, v144
	v_fmac_f32_e32 v34, v88, v148
	v_fmac_f32_e32 v31, v88, v152
	v_fmac_f32_e32 v30, v89, v145
	v_fmac_f32_e32 v34, v89, v149
	v_fmac_f32_e32 v31, v89, v153
	v_fmac_f32_e32 v30, v90, v146
	v_fmac_f32_e32 v34, v90, v150
	v_fmac_f32_e32 v31, v90, v154
	v_fmac_f32_e32 v30, v91, v147
	v_fmac_f32_e32 v34, v91, v151
	v_fmac_f32_e32 v31, v91, v155
	ds_read_b128 v[144:147], v35 offset:64
	ds_read_b128 v[148:151], v35 offset:4160
	ds_read_b128 v[152:155], v35 offset:8256
	s_waitcnt lgkmcnt(3)
	v_fmac_f32_e32 v30, v92, v156
	v_fmac_f32_e32 v34, v92, v160
	v_fmac_f32_e32 v31, v92, v164
	v_fmac_f32_e32 v30, v93, v157
	v_fmac_f32_e32 v34, v93, v161
	v_fmac_f32_e32 v31, v93, v165
	v_fmac_f32_e32 v30, v94, v158
	v_fmac_f32_e32 v34, v94, v162
	v_fmac_f32_e32 v31, v94, v166
	v_fmac_f32_e32 v30, v95, v159
	v_fmac_f32_e32 v34, v95, v163
	v_fmac_f32_e32 v31, v95, v167
	ds_read_b128 v[156:159], v35 offset:80
	ds_read_b128 v[160:163], v35 offset:4176
	ds_read_b128 v[164:167], v35 offset:8272
	s_waitcnt lgkmcnt(3)
	v_fmac_f32_e32 v30, v96, v144
	v_fmac_f32_e32 v34, v96, v148
	v_fmac_f32_e32 v31, v96, v152
	v_fmac_f32_e32 v30, v97, v145
	v_fmac_f32_e32 v34, v97, v149
	v_fmac_f32_e32 v31, v97, v153
	v_fmac_f32_e32 v30, v98, v146
	v_fmac_f32_e32 v34, v98, v150
	v_fmac_f32_e32 v31, v98, v154
	v_fmac_f32_e32 v30, v99, v147
	v_fmac_f32_e32 v34, v99, v151
	v_fmac_f32_e32 v31, v99, v155
	ds_read_b128 v[144:147], v35 offset:96
	ds_read_b128 v[148:151], v35 offset:4192
	ds_read_b128 v[152:155], v35 offset:8288
	s_waitcnt lgkmcnt(3)
	v_fmac_f32_e32 v30, v100, v156
	v_fmac_f32_e32 v34, v100, v160
	v_fmac_f32_e32 v31, v100, v164
	v_fmac_f32_e32 v30, v101, v157
	v_fmac_f32_e32 v34, v101, v161
	v_fmac_f32_e32 v31, v101, v165
	v_fmac_f32_e32 v30, v102, v158
	v_fmac_f32_e32 v34, v102, v162
	v_fmac_f32_e32 v31, v102, v166
	v_fmac_f32_e32 v30, v103, v159
	v_fmac_f32_e32 v34, v103, v163
	v_fmac_f32_e32 v31, v103, v167
	ds_read_b128 v[156:159], v35 offset:112
	ds_read_b128 v[160:163], v35 offset:4208
	ds_read_b128 v[164:167], v35 offset:8304
	s_waitcnt lgkmcnt(3)
	v_fmac_f32_e32 v30, v104, v144
	v_fmac_f32_e32 v34, v104, v148
	v_fmac_f32_e32 v31, v104, v152
	v_fmac_f32_e32 v30, v105, v145
	v_fmac_f32_e32 v34, v105, v149
	v_fmac_f32_e32 v31, v105, v153
	v_fmac_f32_e32 v30, v106, v146
	v_fmac_f32_e32 v34, v106, v150
	v_fmac_f32_e32 v31, v106, v154
	v_fmac_f32_e32 v30, v107, v147
	v_fmac_f32_e32 v34, v107, v151
	v_fmac_f32_e32 v31, v107, v155
	ds_read_b128 v[144:147], v35 offset:128
	ds_read_b128 v[148:151], v35 offset:4224
	ds_read_b128 v[152:155], v35 offset:8320
	s_waitcnt lgkmcnt(3)
	v_fmac_f32_e32 v30, v108, v156
	v_fmac_f32_e32 v34, v108, v160
	v_fmac_f32_e32 v31, v108, v164
	v_fmac_f32_e32 v30, v109, v157
	v_fmac_f32_e32 v34, v109, v161
	v_fmac_f32_e32 v31, v109, v165
	v_fmac_f32_e32 v30, v110, v158
	v_fmac_f32_e32 v34, v110, v162
	v_fmac_f32_e32 v31, v110, v166
	v_fmac_f32_e32 v30, v111, v159
	v_fmac_f32_e32 v34, v111, v163
	v_fmac_f32_e32 v31, v111, v167
	global_load_dword v80, v200, s[98:99]
	s_add_u32 s98, s98, 0x6000
	s_addc_u32 s99, s99, 0
	global_load_dword v81, v200, s[98:99]
	s_add_u32 s98, s98, 0x6000
	s_addc_u32 s99, s99, 0
	global_load_dword v82, v200, s[98:99]
	s_add_u32 s98, s98, 0x6000
	s_addc_u32 s99, s99, 0
	global_load_dword v83, v200, s[98:99]
	s_add_u32 s98, s98, 0x6000
	s_addc_u32 s99, s99, 0
	global_load_dword v84, v200, s[98:99]
	s_add_u32 s98, s98, 0x6000
	s_addc_u32 s99, s99, 0
	global_load_dword v85, v200, s[98:99]
	s_add_u32 s98, s98, 0x6000
	s_addc_u32 s99, s99, 0
	global_load_dword v86, v200, s[98:99]
	s_add_u32 s98, s98, 0x6000
	s_addc_u32 s99, s99, 0
	global_load_dword v87, v200, s[98:99]
	s_add_u32 s98, s98, 0x6000
	s_addc_u32 s99, s99, 0
	global_load_dword v88, v200, s[98:99]
	s_add_u32 s98, s98, 0x6000
	s_addc_u32 s99, s99, 0
	global_load_dword v89, v200, s[98:99]
	s_add_u32 s98, s98, 0x6000
	s_addc_u32 s99, s99, 0
	global_load_dword v90, v200, s[98:99]
	s_add_u32 s98, s98, 0x6000
	s_addc_u32 s99, s99, 0
	global_load_dword v91, v200, s[98:99]
	s_add_u32 s98, s98, 0x6000
	s_addc_u32 s99, s99, 0
	global_load_dword v92, v200, s[98:99]
	s_add_u32 s98, s98, 0x6000
	s_addc_u32 s99, s99, 0
	global_load_dword v93, v200, s[98:99]
	s_add_u32 s98, s98, 0x6000
	s_addc_u32 s99, s99, 0
	global_load_dword v94, v200, s[98:99]
	s_add_u32 s98, s98, 0x6000
	s_addc_u32 s99, s99, 0
	global_load_dword v95, v200, s[98:99]
	s_add_u32 s98, s98, 0x6000
	s_addc_u32 s99, s99, 0
	global_load_dword v96, v200, s[98:99]
	s_add_u32 s98, s98, 0x6000
	s_addc_u32 s99, s99, 0
	global_load_dword v97, v200, s[98:99]
	s_add_u32 s98, s98, 0x6000
	s_addc_u32 s99, s99, 0
	global_load_dword v98, v200, s[98:99]
	s_add_u32 s98, s98, 0x6000
	s_addc_u32 s99, s99, 0
	global_load_dword v99, v200, s[98:99]
	s_add_u32 s98, s98, 0x6000
	s_addc_u32 s99, s99, 0
	global_load_dword v100, v200, s[98:99]
	s_add_u32 s98, s98, 0x6000
	s_addc_u32 s99, s99, 0
	global_load_dword v101, v200, s[98:99]
	s_add_u32 s98, s98, 0x6000
	s_addc_u32 s99, s99, 0
	global_load_dword v102, v200, s[98:99]
	s_add_u32 s98, s98, 0x6000
	s_addc_u32 s99, s99, 0
	global_load_dword v103, v200, s[98:99]
	s_add_u32 s98, s98, 0x6000
	s_addc_u32 s99, s99, 0
	global_load_dword v104, v200, s[98:99]
	s_add_u32 s98, s98, 0x6000
	s_addc_u32 s99, s99, 0
	global_load_dword v105, v200, s[98:99]
	s_add_u32 s98, s98, 0x6000
	s_addc_u32 s99, s99, 0
	global_load_dword v106, v200, s[98:99]
	s_add_u32 s98, s98, 0x6000
	s_addc_u32 s99, s99, 0
	global_load_dword v107, v200, s[98:99]
	s_add_u32 s98, s98, 0x6000
	s_addc_u32 s99, s99, 0
	global_load_dword v108, v200, s[98:99]
	s_add_u32 s98, s98, 0x6000
	s_addc_u32 s99, s99, 0
	global_load_dword v109, v200, s[98:99]
	s_add_u32 s98, s98, 0x6000
	s_addc_u32 s99, s99, 0
	global_load_dword v110, v200, s[98:99]
	s_add_u32 s98, s98, 0x6000
	s_addc_u32 s99, s99, 0
	global_load_dword v111, v200, s[98:99]
	s_add_u32 s98, s98, 0x6000
	s_addc_u32 s99, s99, 0
	s_waitcnt vmcnt(32)
	ds_read_b128 v[156:159], v35 offset:144
	ds_read_b128 v[160:163], v35 offset:4240
	ds_read_b128 v[164:167], v35 offset:8336
	s_waitcnt lgkmcnt(3)
	v_fmac_f32_e32 v30, v112, v144
	v_fmac_f32_e32 v34, v112, v148
	v_fmac_f32_e32 v31, v112, v152
	v_fmac_f32_e32 v30, v113, v145
	v_fmac_f32_e32 v34, v113, v149
	v_fmac_f32_e32 v31, v113, v153
	v_fmac_f32_e32 v30, v114, v146
	v_fmac_f32_e32 v34, v114, v150
	v_fmac_f32_e32 v31, v114, v154
	v_fmac_f32_e32 v30, v115, v147
	v_fmac_f32_e32 v34, v115, v151
	v_fmac_f32_e32 v31, v115, v155
	ds_read_b128 v[144:147], v35 offset:160
	ds_read_b128 v[148:151], v35 offset:4256
	ds_read_b128 v[152:155], v35 offset:8352
	s_waitcnt lgkmcnt(3)
	v_fmac_f32_e32 v30, v116, v156
	v_fmac_f32_e32 v34, v116, v160
	v_fmac_f32_e32 v31, v116, v164
	v_fmac_f32_e32 v30, v117, v157
	v_fmac_f32_e32 v34, v117, v161
	v_fmac_f32_e32 v31, v117, v165
	v_fmac_f32_e32 v30, v118, v158
	v_fmac_f32_e32 v34, v118, v162
	v_fmac_f32_e32 v31, v118, v166
	v_fmac_f32_e32 v30, v119, v159
	v_fmac_f32_e32 v34, v119, v163
	v_fmac_f32_e32 v31, v119, v167
	ds_read_b128 v[156:159], v35 offset:176
	ds_read_b128 v[160:163], v35 offset:4272
	ds_read_b128 v[164:167], v35 offset:8368
	s_waitcnt lgkmcnt(3)
	v_fmac_f32_e32 v30, v120, v144
	v_fmac_f32_e32 v34, v120, v148
	v_fmac_f32_e32 v31, v120, v152
	v_fmac_f32_e32 v30, v121, v145
	v_fmac_f32_e32 v34, v121, v149
	v_fmac_f32_e32 v31, v121, v153
	v_fmac_f32_e32 v30, v122, v146
	v_fmac_f32_e32 v34, v122, v150
	v_fmac_f32_e32 v31, v122, v154
	v_fmac_f32_e32 v30, v123, v147
	v_fmac_f32_e32 v34, v123, v151
	v_fmac_f32_e32 v31, v123, v155
	ds_read_b128 v[144:147], v35 offset:192
	ds_read_b128 v[148:151], v35 offset:4288
	ds_read_b128 v[152:155], v35 offset:8384
	s_waitcnt lgkmcnt(3)
	v_fmac_f32_e32 v30, v124, v156
	v_fmac_f32_e32 v34, v124, v160
	v_fmac_f32_e32 v31, v124, v164
	v_fmac_f32_e32 v30, v125, v157
	v_fmac_f32_e32 v34, v125, v161
	v_fmac_f32_e32 v31, v125, v165
	v_fmac_f32_e32 v30, v126, v158
	v_fmac_f32_e32 v34, v126, v162
	v_fmac_f32_e32 v31, v126, v166
	v_fmac_f32_e32 v30, v127, v159
	v_fmac_f32_e32 v34, v127, v163
	v_fmac_f32_e32 v31, v127, v167
	ds_read_b128 v[156:159], v35 offset:208
	ds_read_b128 v[160:163], v35 offset:4304
	ds_read_b128 v[164:167], v35 offset:8400
	s_waitcnt lgkmcnt(3)
	v_fmac_f32_e32 v30, v128, v144
	v_fmac_f32_e32 v34, v128, v148
	v_fmac_f32_e32 v31, v128, v152
	v_fmac_f32_e32 v30, v129, v145
	v_fmac_f32_e32 v34, v129, v149
	v_fmac_f32_e32 v31, v129, v153
	v_fmac_f32_e32 v30, v130, v146
	v_fmac_f32_e32 v34, v130, v150
	v_fmac_f32_e32 v31, v130, v154
	v_fmac_f32_e32 v30, v131, v147
	v_fmac_f32_e32 v34, v131, v151
	v_fmac_f32_e32 v31, v131, v155
	ds_read_b128 v[144:147], v35 offset:224
	ds_read_b128 v[148:151], v35 offset:4320
	ds_read_b128 v[152:155], v35 offset:8416
	s_waitcnt lgkmcnt(3)
	v_fmac_f32_e32 v30, v132, v156
	v_fmac_f32_e32 v34, v132, v160
	v_fmac_f32_e32 v31, v132, v164
	v_fmac_f32_e32 v30, v133, v157
	v_fmac_f32_e32 v34, v133, v161
	v_fmac_f32_e32 v31, v133, v165
	v_fmac_f32_e32 v30, v134, v158
	v_fmac_f32_e32 v34, v134, v162
	v_fmac_f32_e32 v31, v134, v166
	v_fmac_f32_e32 v30, v135, v159
	v_fmac_f32_e32 v34, v135, v163
	v_fmac_f32_e32 v31, v135, v167
	ds_read_b128 v[156:159], v35 offset:240
	ds_read_b128 v[160:163], v35 offset:4336
	ds_read_b128 v[164:167], v35 offset:8432
	s_waitcnt lgkmcnt(3)
	v_fmac_f32_e32 v30, v136, v144
	v_fmac_f32_e32 v34, v136, v148
	v_fmac_f32_e32 v31, v136, v152
	v_fmac_f32_e32 v30, v137, v145
	v_fmac_f32_e32 v34, v137, v149
	v_fmac_f32_e32 v31, v137, v153
	v_fmac_f32_e32 v30, v138, v146
	v_fmac_f32_e32 v34, v138, v150
	v_fmac_f32_e32 v31, v138, v154
	v_fmac_f32_e32 v30, v139, v147
	v_fmac_f32_e32 v34, v139, v151
	v_fmac_f32_e32 v31, v139, v155
	ds_read_b128 v[144:147], v35 offset:256
	ds_read_b128 v[148:151], v35 offset:4352
	ds_read_b128 v[152:155], v35 offset:8448
	s_waitcnt lgkmcnt(3)
	v_fmac_f32_e32 v30, v140, v156
	v_fmac_f32_e32 v34, v140, v160
	v_fmac_f32_e32 v31, v140, v164
	v_fmac_f32_e32 v30, v141, v157
	v_fmac_f32_e32 v34, v141, v161
	v_fmac_f32_e32 v31, v141, v165
	v_fmac_f32_e32 v30, v142, v158
	v_fmac_f32_e32 v34, v142, v162
	v_fmac_f32_e32 v31, v142, v166
	v_fmac_f32_e32 v30, v143, v159
	v_fmac_f32_e32 v34, v143, v163
	v_fmac_f32_e32 v31, v143, v167
	global_load_dword v112, v200, s[98:99]
	s_add_u32 s98, s98, 0x6000
	s_addc_u32 s99, s99, 0
	global_load_dword v113, v200, s[98:99]
	s_add_u32 s98, s98, 0x6000
	s_addc_u32 s99, s99, 0
	global_load_dword v114, v200, s[98:99]
	s_add_u32 s98, s98, 0x6000
	s_addc_u32 s99, s99, 0
	global_load_dword v115, v200, s[98:99]
	s_add_u32 s98, s98, 0x6000
	s_addc_u32 s99, s99, 0
	global_load_dword v116, v200, s[98:99]
	s_add_u32 s98, s98, 0x6000
	s_addc_u32 s99, s99, 0
	global_load_dword v117, v200, s[98:99]
	s_add_u32 s98, s98, 0x6000
	s_addc_u32 s99, s99, 0
	global_load_dword v118, v200, s[98:99]
	s_add_u32 s98, s98, 0x6000
	s_addc_u32 s99, s99, 0
	global_load_dword v119, v200, s[98:99]
	s_add_u32 s98, s98, 0x6000
	s_addc_u32 s99, s99, 0
	global_load_dword v120, v200, s[98:99]
	s_add_u32 s98, s98, 0x6000
	s_addc_u32 s99, s99, 0
	global_load_dword v121, v200, s[98:99]
	s_add_u32 s98, s98, 0x6000
	s_addc_u32 s99, s99, 0
	global_load_dword v122, v200, s[98:99]
	s_add_u32 s98, s98, 0x6000
	s_addc_u32 s99, s99, 0
	global_load_dword v123, v200, s[98:99]
	s_add_u32 s98, s98, 0x6000
	s_addc_u32 s99, s99, 0
	global_load_dword v124, v200, s[98:99]
	s_add_u32 s98, s98, 0x6000
	s_addc_u32 s99, s99, 0
	global_load_dword v125, v200, s[98:99]
	s_add_u32 s98, s98, 0x6000
	s_addc_u32 s99, s99, 0
	global_load_dword v126, v200, s[98:99]
	s_add_u32 s98, s98, 0x6000
	s_addc_u32 s99, s99, 0
	global_load_dword v127, v200, s[98:99]
	s_add_u32 s98, s98, 0x6000
	s_addc_u32 s99, s99, 0
	global_load_dword v128, v200, s[98:99]
	s_add_u32 s98, s98, 0x6000
	s_addc_u32 s99, s99, 0
	global_load_dword v129, v200, s[98:99]
	s_add_u32 s98, s98, 0x6000
	s_addc_u32 s99, s99, 0
	global_load_dword v130, v200, s[98:99]
	s_add_u32 s98, s98, 0x6000
	s_addc_u32 s99, s99, 0
	global_load_dword v131, v200, s[98:99]
	s_add_u32 s98, s98, 0x6000
	s_addc_u32 s99, s99, 0
	global_load_dword v132, v200, s[98:99]
	s_add_u32 s98, s98, 0x6000
	s_addc_u32 s99, s99, 0
	global_load_dword v133, v200, s[98:99]
	s_add_u32 s98, s98, 0x6000
	s_addc_u32 s99, s99, 0
	global_load_dword v134, v200, s[98:99]
	s_add_u32 s98, s98, 0x6000
	s_addc_u32 s99, s99, 0
	global_load_dword v135, v200, s[98:99]
	s_add_u32 s98, s98, 0x6000
	s_addc_u32 s99, s99, 0
	global_load_dword v136, v200, s[98:99]
	s_add_u32 s98, s98, 0x6000
	s_addc_u32 s99, s99, 0
	global_load_dword v137, v200, s[98:99]
	s_add_u32 s98, s98, 0x6000
	s_addc_u32 s99, s99, 0
	global_load_dword v138, v200, s[98:99]
	s_add_u32 s98, s98, 0x6000
	s_addc_u32 s99, s99, 0
	global_load_dword v139, v200, s[98:99]
	s_add_u32 s98, s98, 0x6000
	s_addc_u32 s99, s99, 0
	global_load_dword v140, v200, s[98:99]
	s_add_u32 s98, s98, 0x6000
	s_addc_u32 s99, s99, 0
	global_load_dword v141, v200, s[98:99]
	s_add_u32 s98, s98, 0x6000
	s_addc_u32 s99, s99, 0
	global_load_dword v142, v200, s[98:99]
	s_add_u32 s98, s98, 0x6000
	s_addc_u32 s99, s99, 0
	global_load_dword v143, v200, s[98:99]
	s_add_u32 s98, s98, 0x6000
	s_addc_u32 s99, s99, 0
	s_waitcnt vmcnt(32)
	ds_read_b128 v[156:159], v35 offset:272
	ds_read_b128 v[160:163], v35 offset:4368
	ds_read_b128 v[164:167], v35 offset:8464
	s_waitcnt lgkmcnt(3)
	v_fmac_f32_e32 v30, v80, v144
	v_fmac_f32_e32 v34, v80, v148
	v_fmac_f32_e32 v31, v80, v152
	v_fmac_f32_e32 v30, v81, v145
	v_fmac_f32_e32 v34, v81, v149
	v_fmac_f32_e32 v31, v81, v153
	v_fmac_f32_e32 v30, v82, v146
	v_fmac_f32_e32 v34, v82, v150
	v_fmac_f32_e32 v31, v82, v154
	v_fmac_f32_e32 v30, v83, v147
	v_fmac_f32_e32 v34, v83, v151
	v_fmac_f32_e32 v31, v83, v155
	ds_read_b128 v[144:147], v35 offset:288
	ds_read_b128 v[148:151], v35 offset:4384
	ds_read_b128 v[152:155], v35 offset:8480
	s_waitcnt lgkmcnt(3)
	v_fmac_f32_e32 v30, v84, v156
	v_fmac_f32_e32 v34, v84, v160
	v_fmac_f32_e32 v31, v84, v164
	v_fmac_f32_e32 v30, v85, v157
	v_fmac_f32_e32 v34, v85, v161
	v_fmac_f32_e32 v31, v85, v165
	v_fmac_f32_e32 v30, v86, v158
	v_fmac_f32_e32 v34, v86, v162
	v_fmac_f32_e32 v31, v86, v166
	v_fmac_f32_e32 v30, v87, v159
	v_fmac_f32_e32 v34, v87, v163
	v_fmac_f32_e32 v31, v87, v167
	ds_read_b128 v[156:159], v35 offset:304
	ds_read_b128 v[160:163], v35 offset:4400
	ds_read_b128 v[164:167], v35 offset:8496
	s_waitcnt lgkmcnt(3)
	v_fmac_f32_e32 v30, v88, v144
	v_fmac_f32_e32 v34, v88, v148
	v_fmac_f32_e32 v31, v88, v152
	v_fmac_f32_e32 v30, v89, v145
	v_fmac_f32_e32 v34, v89, v149
	v_fmac_f32_e32 v31, v89, v153
	v_fmac_f32_e32 v30, v90, v146
	v_fmac_f32_e32 v34, v90, v150
	v_fmac_f32_e32 v31, v90, v154
	v_fmac_f32_e32 v30, v91, v147
	v_fmac_f32_e32 v34, v91, v151
	v_fmac_f32_e32 v31, v91, v155
	ds_read_b128 v[144:147], v35 offset:320
	ds_read_b128 v[148:151], v35 offset:4416
	ds_read_b128 v[152:155], v35 offset:8512
	s_waitcnt lgkmcnt(3)
	v_fmac_f32_e32 v30, v92, v156
	v_fmac_f32_e32 v34, v92, v160
	v_fmac_f32_e32 v31, v92, v164
	v_fmac_f32_e32 v30, v93, v157
	v_fmac_f32_e32 v34, v93, v161
	v_fmac_f32_e32 v31, v93, v165
	v_fmac_f32_e32 v30, v94, v158
	v_fmac_f32_e32 v34, v94, v162
	v_fmac_f32_e32 v31, v94, v166
	v_fmac_f32_e32 v30, v95, v159
	v_fmac_f32_e32 v34, v95, v163
	v_fmac_f32_e32 v31, v95, v167
	ds_read_b128 v[156:159], v35 offset:336
	ds_read_b128 v[160:163], v35 offset:4432
	ds_read_b128 v[164:167], v35 offset:8528
	s_waitcnt lgkmcnt(3)
	v_fmac_f32_e32 v30, v96, v144
	v_fmac_f32_e32 v34, v96, v148
	v_fmac_f32_e32 v31, v96, v152
	v_fmac_f32_e32 v30, v97, v145
	v_fmac_f32_e32 v34, v97, v149
	v_fmac_f32_e32 v31, v97, v153
	v_fmac_f32_e32 v30, v98, v146
	v_fmac_f32_e32 v34, v98, v150
	v_fmac_f32_e32 v31, v98, v154
	v_fmac_f32_e32 v30, v99, v147
	v_fmac_f32_e32 v34, v99, v151
	v_fmac_f32_e32 v31, v99, v155
	ds_read_b128 v[144:147], v35 offset:352
	ds_read_b128 v[148:151], v35 offset:4448
	ds_read_b128 v[152:155], v35 offset:8544
	s_waitcnt lgkmcnt(3)
	v_fmac_f32_e32 v30, v100, v156
	v_fmac_f32_e32 v34, v100, v160
	v_fmac_f32_e32 v31, v100, v164
	v_fmac_f32_e32 v30, v101, v157
	v_fmac_f32_e32 v34, v101, v161
	v_fmac_f32_e32 v31, v101, v165
	v_fmac_f32_e32 v30, v102, v158
	v_fmac_f32_e32 v34, v102, v162
	v_fmac_f32_e32 v31, v102, v166
	v_fmac_f32_e32 v30, v103, v159
	v_fmac_f32_e32 v34, v103, v163
	v_fmac_f32_e32 v31, v103, v167
	ds_read_b128 v[156:159], v35 offset:368
	ds_read_b128 v[160:163], v35 offset:4464
	ds_read_b128 v[164:167], v35 offset:8560
	s_waitcnt lgkmcnt(3)
	v_fmac_f32_e32 v30, v104, v144
	v_fmac_f32_e32 v34, v104, v148
	v_fmac_f32_e32 v31, v104, v152
	v_fmac_f32_e32 v30, v105, v145
	v_fmac_f32_e32 v34, v105, v149
	v_fmac_f32_e32 v31, v105, v153
	v_fmac_f32_e32 v30, v106, v146
	v_fmac_f32_e32 v34, v106, v150
	v_fmac_f32_e32 v31, v106, v154
	v_fmac_f32_e32 v30, v107, v147
	v_fmac_f32_e32 v34, v107, v151
	v_fmac_f32_e32 v31, v107, v155
	ds_read_b128 v[144:147], v35 offset:384
	ds_read_b128 v[148:151], v35 offset:4480
	ds_read_b128 v[152:155], v35 offset:8576
	s_waitcnt lgkmcnt(3)
	v_fmac_f32_e32 v30, v108, v156
	v_fmac_f32_e32 v34, v108, v160
	v_fmac_f32_e32 v31, v108, v164
	v_fmac_f32_e32 v30, v109, v157
	v_fmac_f32_e32 v34, v109, v161
	v_fmac_f32_e32 v31, v109, v165
	v_fmac_f32_e32 v30, v110, v158
	v_fmac_f32_e32 v34, v110, v162
	v_fmac_f32_e32 v31, v110, v166
	v_fmac_f32_e32 v30, v111, v159
	v_fmac_f32_e32 v34, v111, v163
	v_fmac_f32_e32 v31, v111, v167
	s_waitcnt vmcnt(0)
	ds_read_b128 v[156:159], v35 offset:400
	ds_read_b128 v[160:163], v35 offset:4496
	ds_read_b128 v[164:167], v35 offset:8592
	s_waitcnt lgkmcnt(3)
	v_fmac_f32_e32 v30, v112, v144
	v_fmac_f32_e32 v34, v112, v148
	v_fmac_f32_e32 v31, v112, v152
	v_fmac_f32_e32 v30, v113, v145
	v_fmac_f32_e32 v34, v113, v149
	v_fmac_f32_e32 v31, v113, v153
	v_fmac_f32_e32 v30, v114, v146
	v_fmac_f32_e32 v34, v114, v150
	v_fmac_f32_e32 v31, v114, v154
	v_fmac_f32_e32 v30, v115, v147
	v_fmac_f32_e32 v34, v115, v151
	v_fmac_f32_e32 v31, v115, v155
	ds_read_b128 v[144:147], v35 offset:416
	ds_read_b128 v[148:151], v35 offset:4512
	ds_read_b128 v[152:155], v35 offset:8608
	s_waitcnt lgkmcnt(3)
	v_fmac_f32_e32 v30, v116, v156
	v_fmac_f32_e32 v34, v116, v160
	v_fmac_f32_e32 v31, v116, v164
	v_fmac_f32_e32 v30, v117, v157
	v_fmac_f32_e32 v34, v117, v161
	v_fmac_f32_e32 v31, v117, v165
	v_fmac_f32_e32 v30, v118, v158
	v_fmac_f32_e32 v34, v118, v162
	v_fmac_f32_e32 v31, v118, v166
	v_fmac_f32_e32 v30, v119, v159
	v_fmac_f32_e32 v34, v119, v163
	v_fmac_f32_e32 v31, v119, v167
	ds_read_b128 v[156:159], v35 offset:432
	ds_read_b128 v[160:163], v35 offset:4528
	ds_read_b128 v[164:167], v35 offset:8624
	s_waitcnt lgkmcnt(3)
	v_fmac_f32_e32 v30, v120, v144
	v_fmac_f32_e32 v34, v120, v148
	v_fmac_f32_e32 v31, v120, v152
	v_fmac_f32_e32 v30, v121, v145
	v_fmac_f32_e32 v34, v121, v149
	v_fmac_f32_e32 v31, v121, v153
	v_fmac_f32_e32 v30, v122, v146
	v_fmac_f32_e32 v34, v122, v150
	v_fmac_f32_e32 v31, v122, v154
	v_fmac_f32_e32 v30, v123, v147
	v_fmac_f32_e32 v34, v123, v151
	v_fmac_f32_e32 v31, v123, v155
	ds_read_b128 v[144:147], v35 offset:448
	ds_read_b128 v[148:151], v35 offset:4544
	ds_read_b128 v[152:155], v35 offset:8640
	s_waitcnt lgkmcnt(3)
	v_fmac_f32_e32 v30, v124, v156
	v_fmac_f32_e32 v34, v124, v160
	v_fmac_f32_e32 v31, v124, v164
	v_fmac_f32_e32 v30, v125, v157
	v_fmac_f32_e32 v34, v125, v161
	v_fmac_f32_e32 v31, v125, v165
	v_fmac_f32_e32 v30, v126, v158
	v_fmac_f32_e32 v34, v126, v162
	v_fmac_f32_e32 v31, v126, v166
	v_fmac_f32_e32 v30, v127, v159
	v_fmac_f32_e32 v34, v127, v163
	v_fmac_f32_e32 v31, v127, v167
	ds_read_b128 v[156:159], v35 offset:464
	ds_read_b128 v[160:163], v35 offset:4560
	ds_read_b128 v[164:167], v35 offset:8656
	s_waitcnt lgkmcnt(3)
	v_fmac_f32_e32 v30, v128, v144
	v_fmac_f32_e32 v34, v128, v148
	v_fmac_f32_e32 v31, v128, v152
	v_fmac_f32_e32 v30, v129, v145
	v_fmac_f32_e32 v34, v129, v149
	v_fmac_f32_e32 v31, v129, v153
	v_fmac_f32_e32 v30, v130, v146
	v_fmac_f32_e32 v34, v130, v150
	v_fmac_f32_e32 v31, v130, v154
	v_fmac_f32_e32 v30, v131, v147
	v_fmac_f32_e32 v34, v131, v151
	v_fmac_f32_e32 v31, v131, v155
	ds_read_b128 v[144:147], v35 offset:480
	ds_read_b128 v[148:151], v35 offset:4576
	ds_read_b128 v[152:155], v35 offset:8672
	s_waitcnt lgkmcnt(3)
	v_fmac_f32_e32 v30, v132, v156
	v_fmac_f32_e32 v34, v132, v160
	v_fmac_f32_e32 v31, v132, v164
	v_fmac_f32_e32 v30, v133, v157
	v_fmac_f32_e32 v34, v133, v161
	v_fmac_f32_e32 v31, v133, v165
	v_fmac_f32_e32 v30, v134, v158
	v_fmac_f32_e32 v34, v134, v162
	v_fmac_f32_e32 v31, v134, v166
	v_fmac_f32_e32 v30, v135, v159
	v_fmac_f32_e32 v34, v135, v163
	v_fmac_f32_e32 v31, v135, v167
	ds_read_b128 v[156:159], v35 offset:496
	ds_read_b128 v[160:163], v35 offset:4592
	ds_read_b128 v[164:167], v35 offset:8688
	s_waitcnt lgkmcnt(3)
	v_fmac_f32_e32 v30, v136, v144
	v_fmac_f32_e32 v34, v136, v148
	v_fmac_f32_e32 v31, v136, v152
	v_fmac_f32_e32 v30, v137, v145
	v_fmac_f32_e32 v34, v137, v149
	v_fmac_f32_e32 v31, v137, v153
	v_fmac_f32_e32 v30, v138, v146
	v_fmac_f32_e32 v34, v138, v150
	v_fmac_f32_e32 v31, v138, v154
	v_fmac_f32_e32 v30, v139, v147
	v_fmac_f32_e32 v34, v139, v151
	v_fmac_f32_e32 v31, v139, v155
	s_waitcnt lgkmcnt(0)
	v_fmac_f32_e32 v30, v140, v156
	v_fmac_f32_e32 v34, v140, v160
	v_fmac_f32_e32 v31, v140, v164
	v_fmac_f32_e32 v30, v141, v157
	v_fmac_f32_e32 v34, v141, v161
	v_fmac_f32_e32 v31, v141, v165
	v_fmac_f32_e32 v30, v142, v158
	v_fmac_f32_e32 v34, v142, v162
	v_fmac_f32_e32 v31, v142, v166
	v_fmac_f32_e32 v30, v143, v159
	v_fmac_f32_e32 v34, v143, v163
	v_fmac_f32_e32 v31, v143, v167
	ds_write2st64_b32 v19, v30, v34 offset0:52 offset1:53
	ds_write_b32 v19, v31 offset:13824
	s_waitcnt lgkmcnt(0)
	s_barrier
	s_and_saveexec_b64 s[4:5], vcc
	s_cbranch_execz .LBB0_27
	ds_read_b64 v[28:29], v23 offset:152
	s_mul_i32 s20, s39, 0x1800
	s_add_i32 s20, s20, s12
	v_or_b32_e32 v30, s20, v198
	v_ashrrev_i32_e32 v31, 31, v30
	s_waitcnt lgkmcnt(0)
	v_readfirstlane_b32 s21, v28
	v_readfirstlane_b32 s40, v29
	v_mov_b64_e32 v[40:41], s[10:11]
	v_mov_b32_e32 v28, s21
	v_mov_b32_e32 v29, s40
	v_lshl_add_u64 v[28:29], v[30:31], 2, v[28:29]
	global_load_dword v42, v[28:29], off
	ds_read2st64_b32 v[28:29], v33 offset0:52 offset1:55
	ds_read2st64_b32 v[30:31], v33 offset0:58 offset1:61
	ds_read2st64_b32 v[34:35], v33 offset0:64 offset1:67
	ds_read2st64_b32 v[36:37], v33 offset0:70 offset1:73
	v_mad_u64_u32 v[38:39], s[20:21], s39, 3, v[18:19]
	s_waitcnt lgkmcnt(3)
	v_add_f32_e32 v28, 0, v28
	v_add_f32_e32 v28, v28, v29
	s_waitcnt lgkmcnt(2)
	v_add_f32_e32 v28, v28, v30
	v_add_f32_e32 v28, v28, v31
	s_waitcnt lgkmcnt(1)
	v_add_f32_e32 v28, v28, v34
	v_add_f32_e32 v28, v28, v35
	v_mad_i64_i32 v[38:39], s[20:21], v38, s23, v[40:41]
	s_waitcnt lgkmcnt(0)
	v_add_f32_e32 v28, v28, v36
	v_lshl_add_u64 v[38:39], s[12:13], 2, v[38:39]
	v_add_f32_e32 v28, v28, v37
	s_waitcnt vmcnt(0)
	v_add_f32_e32 v30, v28, v42
	v_lshl_add_u64 v[28:29], v[38:39], 0, v[22:23]
	global_store_dword v[28:29], v30, off
	s_branch .LBB0_27
